# offset-preserving tile transitions in plain and swiglu GEMMs: halves no longer re-align at the epilogue (extra barrier only on the last tile), trailing epilogue overlaps leading next-tile first phase
# baseline (speedup 1.0000x reference)
.Lg1_loop:
	s_add_u32 s44, s42, 0x100
	s_addc_u32 s45, s43, 0
	s_cmp_eq_u32 s63, s54
	s_cselect_b32 s50, s26, s44
	s_cselect_b32 s51, s5, s45
	s_cselect_b32 s48, s27, s28
	s_cselect_b32 s49, s23, s29
	s_add_u32 s46, s42, 0x80
	s_addc_u32 s47, s43, 0
	s_mov_b32 m0, s60
	s_add_u32 s42, s42, s53
	s_addc_u32 s43, s43, 0
	global_load_lds_dwordx4 v0, s[46:47]
	s_mov_b32 m0, s61
	ds_read_b128 v[164:167], v244
	global_load_lds_dwordx4 v142, s[46:47]
	ds_read_b128 v[168:171], v244 offset:1024
	ds_read_b128 v[188:191], v244 offset:2048
	ds_read_b128 v[192:195], v244 offset:3072
	ds_read_b128 v[196:199], v244 offset:16384
	ds_read_b128 v[200:203], v244 offset:17408
	ds_read_b128 v[204:207], v244 offset:18432
	ds_read_b128 v[208:211], v244 offset:19456
	s_add_i32 m0, s56, 0xc000
	ds_read_b128 v[212:215], v160
	global_load_lds_dwordx4 v0, s[42:43]
	s_add_i32 m0, s56, 0xe000
	ds_read_b128 v[216:219], v160 offset:1024
	global_load_lds_dwordx4 v142, s[42:43]
	ds_read_b128 v[220:223], v160 offset:2048
	ds_read_b128 v[224:227], v160 offset:3072
	ds_read_b128 v[228:231], v160 offset:4096
	ds_read_b128 v[232:235], v160 offset:5120
	ds_read_b128 v[236:239], v160 offset:6144
	ds_read_b128 v[240:243], v160 offset:7168
	s_waitcnt vmcnt(8)
	s_waitcnt lgkmcnt(8)
	s_barrier
	s_setprio 1
	s_waitcnt lgkmcnt(0)
	v_mfma_f32_16x16x32_bf16 v[128:131], v[164:167], v[212:215], v[128:131]
	v_mfma_f32_16x16x32_bf16 v[124:127], v[188:191], v[212:215], v[124:127]
	v_mfma_f32_16x16x32_bf16 v[112:115], v[164:167], v[220:223], v[112:115]
	v_mfma_f32_16x16x32_bf16 v[108:111], v[188:191], v[220:223], v[108:111]
	v_mfma_f32_16x16x32_bf16 v[96:99], v[164:167], v[228:231], v[96:99]
	v_mfma_f32_16x16x32_bf16 v[92:95], v[188:191], v[228:231], v[92:95]
	v_mfma_f32_16x16x32_bf16 v[80:83], v[164:167], v[236:239], v[80:83]
	v_mfma_f32_16x16x32_bf16 v[76:79], v[188:191], v[236:239], v[76:79]
	v_mfma_f32_16x16x32_bf16 v[128:131], v[168:171], v[216:219], v[128:131]
	v_mfma_f32_16x16x32_bf16 v[124:127], v[192:195], v[216:219], v[124:127]
	v_mfma_f32_16x16x32_bf16 v[112:115], v[168:171], v[224:227], v[112:115]
	v_mfma_f32_16x16x32_bf16 v[108:111], v[192:195], v[224:227], v[108:111]
	v_mfma_f32_16x16x32_bf16 v[96:99], v[168:171], v[232:235], v[96:99]
	v_mfma_f32_16x16x32_bf16 v[92:95], v[192:195], v[232:235], v[92:95]
	v_mfma_f32_16x16x32_bf16 v[80:83], v[168:171], v[240:243], v[80:83]
	v_mfma_f32_16x16x32_bf16 v[76:79], v[192:195], v[240:243], v[76:79]
	s_setprio 0
	s_setprio 1
	v_mfma_f32_16x16x32_bf16 v[120:123], v[196:199], v[212:215], v[120:123]
	v_mfma_f32_16x16x32_bf16 v[116:119], v[204:207], v[212:215], v[116:119]
	v_mfma_f32_16x16x32_bf16 v[104:107], v[196:199], v[220:223], v[104:107]
	v_mfma_f32_16x16x32_bf16 v[100:103], v[204:207], v[220:223], v[100:103]
	v_mfma_f32_16x16x32_bf16 v[88:91], v[196:199], v[228:231], v[88:91]
	v_mfma_f32_16x16x32_bf16 v[84:87], v[204:207], v[228:231], v[84:87]
	v_mfma_f32_16x16x32_bf16 v[72:75], v[196:199], v[236:239], v[72:75]
	v_mfma_f32_16x16x32_bf16 v[68:71], v[204:207], v[236:239], v[68:71]
	v_mfma_f32_16x16x32_bf16 v[120:123], v[200:203], v[216:219], v[120:123]
	v_mfma_f32_16x16x32_bf16 v[116:119], v[208:211], v[216:219], v[116:119]
	v_mfma_f32_16x16x32_bf16 v[104:107], v[200:203], v[224:227], v[104:107]
	v_mfma_f32_16x16x32_bf16 v[100:103], v[208:211], v[224:227], v[100:103]
	v_mfma_f32_16x16x32_bf16 v[88:91], v[200:203], v[232:235], v[88:91]
	v_mfma_f32_16x16x32_bf16 v[84:87], v[208:211], v[232:235], v[84:87]
	v_mfma_f32_16x16x32_bf16 v[72:75], v[200:203], v[240:243], v[72:75]
	v_mfma_f32_16x16x32_bf16 v[68:71], v[208:211], v[240:243], v[68:71]
	s_setprio 0
	s_barrier
	s_add_i32 m0, s69, 0x10000
	s_add_u32 s42, s48, s90
	s_addc_u32 s43, s49, 0
	global_load_lds_dwordx4 v140, s[48:49]
	s_add_i32 m0, s69, 0x12000
	ds_read_b128 v[212:215], v160 offset:16384
	global_load_lds_dwordx4 v144, s[48:49]
	s_add_i32 m0, s69, 0x14000
	ds_read_b128 v[216:219], v160 offset:17408
	global_load_lds_dwordx4 v140, s[42:43]
	s_add_i32 m0, s69, 0x16000
	ds_read_b128 v[220:223], v160 offset:18432
	global_load_lds_dwordx4 v144, s[42:43]
	ds_read_b128 v[224:227], v160 offset:19456
	ds_read_b128 v[228:231], v160 offset:20480
	ds_read_b128 v[232:235], v160 offset:21504
	ds_read_b128 v[236:239], v160 offset:22528
	ds_read_b128 v[240:243], v160 offset:23552
	s_waitcnt vmcnt(6)
	s_waitcnt lgkmcnt(0)
	s_barrier
	s_setprio 1
	s_waitcnt lgkmcnt(0)
	v_mfma_f32_16x16x32_bf16 v[64:67], v[164:167], v[212:215], v[64:67]
	v_mfma_f32_16x16x32_bf16 v[60:63], v[188:191], v[212:215], v[60:63]
	v_mfma_f32_16x16x32_bf16 v[48:51], v[164:167], v[220:223], v[48:51]
	v_mfma_f32_16x16x32_bf16 v[44:47], v[188:191], v[220:223], v[44:47]
	v_mfma_f32_16x16x32_bf16 v[32:35], v[164:167], v[228:231], v[32:35]
	v_mfma_f32_16x16x32_bf16 v[28:31], v[188:191], v[228:231], v[28:31]
	v_mfma_f32_16x16x32_bf16 v[16:19], v[164:167], v[236:239], v[16:19]
	v_mfma_f32_16x16x32_bf16 v[12:15], v[188:191], v[236:239], v[12:15]
	v_mfma_f32_16x16x32_bf16 v[64:67], v[168:171], v[216:219], v[64:67]
	v_mfma_f32_16x16x32_bf16 v[60:63], v[192:195], v[216:219], v[60:63]
	v_mfma_f32_16x16x32_bf16 v[48:51], v[168:171], v[224:227], v[48:51]
	v_mfma_f32_16x16x32_bf16 v[44:47], v[192:195], v[224:227], v[44:47]
	v_mfma_f32_16x16x32_bf16 v[32:35], v[168:171], v[232:235], v[32:35]
	v_mfma_f32_16x16x32_bf16 v[28:31], v[192:195], v[232:235], v[28:31]
	v_mfma_f32_16x16x32_bf16 v[16:19], v[168:171], v[240:243], v[16:19]
	v_mfma_f32_16x16x32_bf16 v[12:15], v[192:195], v[240:243], v[12:15]
	s_setprio 0
	s_setprio 1
	v_mfma_f32_16x16x32_bf16 v[56:59], v[196:199], v[212:215], v[56:59]
	v_mfma_f32_16x16x32_bf16 v[52:55], v[204:207], v[212:215], v[52:55]
	v_mfma_f32_16x16x32_bf16 v[40:43], v[196:199], v[220:223], v[40:43]
	v_mfma_f32_16x16x32_bf16 v[36:39], v[204:207], v[220:223], v[36:39]
	v_mfma_f32_16x16x32_bf16 v[24:27], v[196:199], v[228:231], v[24:27]
	v_mfma_f32_16x16x32_bf16 v[20:23], v[204:207], v[228:231], v[20:23]
	v_mfma_f32_16x16x32_bf16 v[8:11], v[196:199], v[236:239], v[8:11]
	v_mfma_f32_16x16x32_bf16 v[4:7], v[204:207], v[236:239], v[4:7]
	v_mfma_f32_16x16x32_bf16 v[56:59], v[200:203], v[216:219], v[56:59]
	v_mfma_f32_16x16x32_bf16 v[52:55], v[208:211], v[216:219], v[52:55]
	v_mfma_f32_16x16x32_bf16 v[40:43], v[200:203], v[224:227], v[40:43]
	v_mfma_f32_16x16x32_bf16 v[36:39], v[208:211], v[224:227], v[36:39]
	v_mfma_f32_16x16x32_bf16 v[24:27], v[200:203], v[232:235], v[24:27]
	v_mfma_f32_16x16x32_bf16 v[20:23], v[208:211], v[232:235], v[20:23]
	v_mfma_f32_16x16x32_bf16 v[8:11], v[200:203], v[240:243], v[8:11]
	v_mfma_f32_16x16x32_bf16 v[4:7], v[208:211], v[240:243], v[4:7]
	s_setprio 0
	s_barrier
	s_mov_b32 m0, s56
	s_add_u32 s42, s50, s90
	s_addc_u32 s43, s51, 0
	global_load_lds_dwordx4 v0, s[50:51]
	s_mov_b32 m0, s57
	ds_read_b128 v[164:167], v244 offset:32768
	global_load_lds_dwordx4 v142, s[50:51]
	ds_read_b128 v[168:171], v244 offset:33792
	ds_read_b128 v[188:191], v244 offset:34816
	ds_read_b128 v[192:195], v244 offset:35840
	ds_read_b128 v[196:199], v244 offset:49152
	ds_read_b128 v[200:203], v244 offset:50176
	ds_read_b128 v[204:207], v244 offset:51200
	ds_read_b128 v[208:211], v244 offset:52224
	s_mov_b32 m0, s58
	ds_read_b128 v[212:215], v160 offset:32768
	global_load_lds_dwordx4 v0, s[42:43]
	s_mov_b32 m0, s59
	ds_read_b128 v[216:219], v160 offset:33792
	global_load_lds_dwordx4 v142, s[42:43]
	ds_read_b128 v[220:223], v160 offset:34816
	ds_read_b128 v[224:227], v160 offset:35840
	ds_read_b128 v[228:231], v160 offset:36864
	ds_read_b128 v[232:235], v160 offset:37888
	ds_read_b128 v[236:239], v160 offset:38912
	ds_read_b128 v[240:243], v160 offset:39936
	s_waitcnt vmcnt(8)
	s_waitcnt lgkmcnt(8)
	s_barrier
	s_setprio 1
	s_waitcnt lgkmcnt(0)
	v_mfma_f32_16x16x32_bf16 v[128:131], v[164:167], v[212:215], v[128:131]
	v_mfma_f32_16x16x32_bf16 v[124:127], v[188:191], v[212:215], v[124:127]
	v_mfma_f32_16x16x32_bf16 v[112:115], v[164:167], v[220:223], v[112:115]
	v_mfma_f32_16x16x32_bf16 v[108:111], v[188:191], v[220:223], v[108:111]
	v_mfma_f32_16x16x32_bf16 v[96:99], v[164:167], v[228:231], v[96:99]
	v_mfma_f32_16x16x32_bf16 v[92:95], v[188:191], v[228:231], v[92:95]
	v_mfma_f32_16x16x32_bf16 v[80:83], v[164:167], v[236:239], v[80:83]
	v_mfma_f32_16x16x32_bf16 v[76:79], v[188:191], v[236:239], v[76:79]
	v_mfma_f32_16x16x32_bf16 v[128:131], v[168:171], v[216:219], v[128:131]
	v_mfma_f32_16x16x32_bf16 v[124:127], v[192:195], v[216:219], v[124:127]
	v_mfma_f32_16x16x32_bf16 v[112:115], v[168:171], v[224:227], v[112:115]
	v_mfma_f32_16x16x32_bf16 v[108:111], v[192:195], v[224:227], v[108:111]
	v_mfma_f32_16x16x32_bf16 v[96:99], v[168:171], v[232:235], v[96:99]
	v_mfma_f32_16x16x32_bf16 v[92:95], v[192:195], v[232:235], v[92:95]
	v_mfma_f32_16x16x32_bf16 v[80:83], v[168:171], v[240:243], v[80:83]
	v_mfma_f32_16x16x32_bf16 v[76:79], v[192:195], v[240:243], v[76:79]
	s_setprio 0
	s_setprio 1
	v_mfma_f32_16x16x32_bf16 v[120:123], v[196:199], v[212:215], v[120:123]
	v_mfma_f32_16x16x32_bf16 v[116:119], v[204:207], v[212:215], v[116:119]
	v_mfma_f32_16x16x32_bf16 v[104:107], v[196:199], v[220:223], v[104:107]
	v_mfma_f32_16x16x32_bf16 v[100:103], v[204:207], v[220:223], v[100:103]
	v_mfma_f32_16x16x32_bf16 v[88:91], v[196:199], v[228:231], v[88:91]
	v_mfma_f32_16x16x32_bf16 v[84:87], v[204:207], v[228:231], v[84:87]
	v_mfma_f32_16x16x32_bf16 v[72:75], v[196:199], v[236:239], v[72:75]
	v_mfma_f32_16x16x32_bf16 v[68:71], v[204:207], v[236:239], v[68:71]
	v_mfma_f32_16x16x32_bf16 v[120:123], v[200:203], v[216:219], v[120:123]
	v_mfma_f32_16x16x32_bf16 v[116:119], v[208:211], v[216:219], v[116:119]
	v_mfma_f32_16x16x32_bf16 v[104:107], v[200:203], v[224:227], v[104:107]
	v_mfma_f32_16x16x32_bf16 v[100:103], v[208:211], v[224:227], v[100:103]
	v_mfma_f32_16x16x32_bf16 v[88:91], v[200:203], v[232:235], v[88:91]
	v_mfma_f32_16x16x32_bf16 v[84:87], v[208:211], v[232:235], v[84:87]
	v_mfma_f32_16x16x32_bf16 v[72:75], v[200:203], v[240:243], v[72:75]
	v_mfma_f32_16x16x32_bf16 v[68:71], v[208:211], v[240:243], v[68:71]
	s_setprio 0
	s_barrier
	s_add_u32 s42, s48, 0x80
	s_addc_u32 s43, s49, 0
	s_add_i32 m0, s69, 0x18000
	s_add_u32 s46, s48, s53
	s_addc_u32 s47, s49, 0
	global_load_lds_dwordx4 v140, s[42:43]
	s_add_i32 m0, s69, 0x1a000
	ds_read_b128 v[212:215], v160 offset:49152
	global_load_lds_dwordx4 v144, s[42:43]
	s_add_i32 m0, s69, 0x1c000
	ds_read_b128 v[216:219], v160 offset:50176
	global_load_lds_dwordx4 v140, s[46:47]
	s_add_i32 m0, s69, 0x1e000
	ds_read_b128 v[220:223], v160 offset:51200
	global_load_lds_dwordx4 v144, s[46:47]
	ds_read_b128 v[224:227], v160 offset:52224
	ds_read_b128 v[228:231], v160 offset:53248
	ds_read_b128 v[232:235], v160 offset:54272
	ds_read_b128 v[236:239], v160 offset:55296
	ds_read_b128 v[240:243], v160 offset:56320
	s_waitcnt vmcnt(6)
	s_waitcnt lgkmcnt(0)
	s_barrier
	s_setprio 1
	s_waitcnt lgkmcnt(0)
	v_mfma_f32_16x16x32_bf16 v[64:67], v[164:167], v[212:215], v[64:67]
	v_mfma_f32_16x16x32_bf16 v[60:63], v[188:191], v[212:215], v[60:63]
	v_mfma_f32_16x16x32_bf16 v[48:51], v[164:167], v[220:223], v[48:51]
	v_mfma_f32_16x16x32_bf16 v[44:47], v[188:191], v[220:223], v[44:47]
	v_mfma_f32_16x16x32_bf16 v[32:35], v[164:167], v[228:231], v[32:35]
	v_mfma_f32_16x16x32_bf16 v[28:31], v[188:191], v[228:231], v[28:31]
	v_mfma_f32_16x16x32_bf16 v[16:19], v[164:167], v[236:239], v[16:19]
	v_mfma_f32_16x16x32_bf16 v[12:15], v[188:191], v[236:239], v[12:15]
	v_mfma_f32_16x16x32_bf16 v[64:67], v[168:171], v[216:219], v[64:67]
	v_mfma_f32_16x16x32_bf16 v[60:63], v[192:195], v[216:219], v[60:63]
	v_mfma_f32_16x16x32_bf16 v[48:51], v[168:171], v[224:227], v[48:51]
	v_mfma_f32_16x16x32_bf16 v[44:47], v[192:195], v[224:227], v[44:47]
	v_mfma_f32_16x16x32_bf16 v[32:35], v[168:171], v[232:235], v[32:35]
	v_mfma_f32_16x16x32_bf16 v[28:31], v[192:195], v[232:235], v[28:31]
	v_mfma_f32_16x16x32_bf16 v[16:19], v[168:171], v[240:243], v[16:19]
	v_mfma_f32_16x16x32_bf16 v[12:15], v[192:195], v[240:243], v[12:15]
	s_setprio 0
	s_setprio 1
	v_mfma_f32_16x16x32_bf16 v[56:59], v[196:199], v[212:215], v[56:59]
	v_mfma_f32_16x16x32_bf16 v[52:55], v[204:207], v[212:215], v[52:55]
	v_mfma_f32_16x16x32_bf16 v[40:43], v[196:199], v[220:223], v[40:43]
	v_mfma_f32_16x16x32_bf16 v[36:39], v[204:207], v[220:223], v[36:39]
	v_mfma_f32_16x16x32_bf16 v[24:27], v[196:199], v[228:231], v[24:27]
	v_mfma_f32_16x16x32_bf16 v[20:23], v[204:207], v[228:231], v[20:23]
	v_mfma_f32_16x16x32_bf16 v[8:11], v[196:199], v[236:239], v[8:11]
	v_mfma_f32_16x16x32_bf16 v[4:7], v[204:207], v[236:239], v[4:7]
	v_mfma_f32_16x16x32_bf16 v[56:59], v[200:203], v[216:219], v[56:59]
	v_mfma_f32_16x16x32_bf16 v[52:55], v[208:211], v[216:219], v[52:55]
	v_mfma_f32_16x16x32_bf16 v[40:43], v[200:203], v[224:227], v[40:43]
	v_mfma_f32_16x16x32_bf16 v[36:39], v[208:211], v[224:227], v[36:39]
	v_mfma_f32_16x16x32_bf16 v[24:27], v[200:203], v[232:235], v[24:27]
	v_mfma_f32_16x16x32_bf16 v[20:23], v[208:211], v[232:235], v[20:23]
	v_mfma_f32_16x16x32_bf16 v[8:11], v[200:203], v[240:243], v[8:11]
	v_mfma_f32_16x16x32_bf16 v[4:7], v[208:211], v[240:243], v[4:7]
	s_setprio 0
	s_barrier
	s_add_i32 s63, s63, 2
	s_add_u32 s28, s28, 0x100
	s_addc_u32 s29, s29, 0
	s_cmp_gt_u32 s63, s55
	s_mov_b64 s[42:43], s[44:45]
	s_cbranch_scc0 .Lg1_loop
	v_readlane_b32 s5, v250, 0
	v_readlane_b32 s23, v250, 1
	v_readlane_b32 s26, v250, 2
	v_readlane_b32 s27, v250, 3
	v_readlane_b32 s28, v250, 4
	v_readlane_b32 s29, v250, 5
	v_readlane_b32 s42, v250, 6
	v_readlane_b32 s43, v250, 7
	v_readlane_b32 s44, v250, 8
	v_readlane_b32 s45, v250, 9
	v_readlane_b32 s46, v250, 10
	v_readlane_b32 s47, v250, 11
	v_readlane_b32 s48, v250, 12
	v_readlane_b32 s49, v250, 13
	v_readlane_b32 s50, v250, 14
	v_readlane_b32 s51, v250, 15
	v_readlane_b32 s53, v250, 16
	v_readlane_b32 s54, v250, 17
	v_readlane_b32 s55, v250, 18
	v_readlane_b32 s56, v250, 19
	v_readlane_b32 s57, v250, 20
	v_readlane_b32 s58, v250, 21
	v_readlane_b32 s59, v250, 22
	v_readlane_b32 s60, v250, 23
	v_readlane_b32 s61, v250, 24
	v_readlane_b32 s63, v250, 25
	v_readlane_b32 s64, v250, 26
	v_readlane_b32 s65, v250, 27
	s_and_b64 vcc, s[14:15], s[40:41]
	s_and_b64 vcc, exec, vcc
	s_cbranch_vccz .LBB0_419
	s_barrier

.LBB0_435:
	s_nop 0
	v_add_u32_e32 v20, 0xb0, v150
	v_mad_i64_i32 v[20:21], s[8:9], v20, s22, 0
	v_lshl_add_u64 v[20:21], v[20:21], 1, s[4:5]
	v_lshl_add_u64 v[20:21], v[154:155], 1, v[20:21]
	s_waitcnt vmcnt(0)
	v_pk_mul_f32 v[18:19], v[18:19], v[36:37] op_sel_hi:[1,0]
	v_pk_mul_f32 v[16:17], v[16:17], v[36:37] op_sel_hi:[1,0]
	v_pk_mul_f32 v[22:23], v[14:15], v[36:37] op_sel_hi:[1,0]
	v_pk_mul_f32 v[14:15], v[12:13], v[36:37] op_sel_hi:[1,0]
	v_cvt_pk_bf16_f32 v12, v16, v17
	v_cvt_pk_bf16_f32 v13, v18, v19
	s_and_b64 vcc, exec, s[40:41]
	v_cvt_pk_bf16_f32 v14, v14, v15
	v_cvt_pk_bf16_f32 v15, v22, v23
	global_store_dwordx4 v[20:21], v[12:15], off
	s_mov_b64 s[40:41], -1
	v_pk_mul_f32 v[10:11], v[10:11], v[36:37] op_sel_hi:[1,0]
	v_pk_mul_f32 v[12:13], v[6:7], v[36:37] op_sel_hi:[1,0]
	v_pk_mul_f32 v[6:7], v[4:5], v[36:37] op_sel_hi:[1,0]
	v_pk_mul_f32 v[8:9], v[8:9], v[36:37] op_sel_hi:[1,0]
	s_nop 0
	v_cvt_pk_bf16_f32 v4, v8, v9
	v_cvt_pk_bf16_f32 v5, v10, v11
	v_cvt_pk_bf16_f32 v6, v6, v7
	v_cvt_pk_bf16_f32 v7, v12, v13
	global_store_dwordx4 v[20:21], v[4:7], off offset:256
	s_cbranch_vccnz .LBB0_408
	s_branch .LBB0_407

.LBB0_500:
	s_add_u32 s44, s42, 0x100
	s_addc_u32 s45, s43, 0
	s_cmp_eq_u32 s63, 12
	s_cselect_b32 s50, s26, s44
	s_cselect_b32 s51, s5, s45
	s_cselect_b32 s48, s27, s28
	s_cselect_b32 s49, s23, s29
	s_add_u32 s46, s42, 0x80
	s_addc_u32 s47, s43, 0
	s_mov_b32 m0, s60
	s_add_u32 s42, s42, 0x40080
	s_addc_u32 s43, s43, 0
	global_load_lds_dwordx4 v144, s[46:47]
	s_mov_b32 m0, s61
	ds_read_b128 v[146:149], v240
	global_load_lds_dwordx4 v140, s[46:47]
	ds_read_b128 v[150:153], v240 offset:1024
	ds_read_b128 v[154:157], v240 offset:2048
	ds_read_b128 v[158:161], v240 offset:3072
	ds_read_b128 v[162:165], v240 offset:16384
	ds_read_b128 v[166:169], v240 offset:17408
	ds_read_b128 v[170:173], v240 offset:18432
	ds_read_b128 v[186:189], v240 offset:19456
	s_add_i32 m0, s56, 0xc000
	ds_read_b128 v[190:193], v132
	global_load_lds_dwordx4 v144, s[42:43]
	s_add_i32 m0, s56, 0xe000
	ds_read_b128 v[194:197], v132 offset:1024
	global_load_lds_dwordx4 v140, s[42:43]
	ds_read_b128 v[198:201], v132 offset:2048
	ds_read_b128 v[202:205], v132 offset:3072
	ds_read_b128 v[206:209], v132 offset:4096
	ds_read_b128 v[210:213], v132 offset:5120
	ds_read_b128 v[214:217], v132 offset:6144
	ds_read_b128 v[218:221], v132 offset:7168
	s_waitcnt vmcnt(8)
	s_waitcnt lgkmcnt(8)
	s_barrier
	s_setprio 1
	s_waitcnt lgkmcnt(0)
	v_mfma_f32_16x16x32_bf16 v[128:131], v[146:149], v[190:193], v[128:131]
	v_mfma_f32_16x16x32_bf16 v[124:127], v[154:157], v[190:193], v[124:127]
	v_mfma_f32_16x16x32_bf16 v[112:115], v[146:149], v[198:201], v[112:115]
	v_mfma_f32_16x16x32_bf16 v[108:111], v[154:157], v[198:201], v[108:111]
	v_mfma_f32_16x16x32_bf16 v[96:99], v[146:149], v[206:209], v[96:99]
	v_mfma_f32_16x16x32_bf16 v[92:95], v[154:157], v[206:209], v[92:95]
	v_mfma_f32_16x16x32_bf16 v[80:83], v[146:149], v[214:217], v[80:83]
	v_mfma_f32_16x16x32_bf16 v[76:79], v[154:157], v[214:217], v[76:79]
	v_mfma_f32_16x16x32_bf16 v[128:131], v[150:153], v[194:197], v[128:131]
	v_mfma_f32_16x16x32_bf16 v[124:127], v[158:161], v[194:197], v[124:127]
	v_mfma_f32_16x16x32_bf16 v[112:115], v[150:153], v[202:205], v[112:115]
	v_mfma_f32_16x16x32_bf16 v[108:111], v[158:161], v[202:205], v[108:111]
	v_mfma_f32_16x16x32_bf16 v[96:99], v[150:153], v[210:213], v[96:99]
	v_mfma_f32_16x16x32_bf16 v[92:95], v[158:161], v[210:213], v[92:95]
	v_mfma_f32_16x16x32_bf16 v[80:83], v[150:153], v[218:221], v[80:83]
	v_mfma_f32_16x16x32_bf16 v[76:79], v[158:161], v[218:221], v[76:79]
	s_setprio 0
	s_setprio 1
	v_mfma_f32_16x16x32_bf16 v[120:123], v[162:165], v[190:193], v[120:123]
	v_mfma_f32_16x16x32_bf16 v[116:119], v[170:173], v[190:193], v[116:119]
	v_mfma_f32_16x16x32_bf16 v[104:107], v[162:165], v[198:201], v[104:107]
	v_mfma_f32_16x16x32_bf16 v[100:103], v[170:173], v[198:201], v[100:103]
	v_mfma_f32_16x16x32_bf16 v[88:91], v[162:165], v[206:209], v[88:91]
	v_mfma_f32_16x16x32_bf16 v[84:87], v[170:173], v[206:209], v[84:87]
	v_mfma_f32_16x16x32_bf16 v[72:75], v[162:165], v[214:217], v[72:75]
	v_mfma_f32_16x16x32_bf16 v[68:71], v[170:173], v[214:217], v[68:71]
	v_mfma_f32_16x16x32_bf16 v[120:123], v[166:169], v[194:197], v[120:123]
	v_mfma_f32_16x16x32_bf16 v[116:119], v[186:189], v[194:197], v[116:119]
	v_mfma_f32_16x16x32_bf16 v[104:107], v[166:169], v[202:205], v[104:107]
	v_mfma_f32_16x16x32_bf16 v[100:103], v[186:189], v[202:205], v[100:103]
	v_mfma_f32_16x16x32_bf16 v[88:91], v[166:169], v[210:213], v[88:91]
	v_mfma_f32_16x16x32_bf16 v[84:87], v[186:189], v[210:213], v[84:87]
	v_mfma_f32_16x16x32_bf16 v[72:75], v[166:169], v[218:221], v[72:75]
	v_mfma_f32_16x16x32_bf16 v[68:71], v[186:189], v[218:221], v[68:71]
	s_setprio 0
	s_barrier
	s_add_i32 m0, s69, 0x10000
	s_add_u32 s42, s48, 0x40000
	s_addc_u32 s43, s49, 0
	global_load_lds_dwordx4 v142, s[48:49]
	s_add_i32 m0, s69, 0x12000
	ds_read_b128 v[190:193], v132 offset:16384
	global_load_lds_dwordx4 v0, s[48:49]
	s_add_i32 m0, s69, 0x14000
	ds_read_b128 v[194:197], v132 offset:17408
	global_load_lds_dwordx4 v142, s[42:43]
	s_add_i32 m0, s69, 0x16000
	ds_read_b128 v[198:201], v132 offset:18432
	global_load_lds_dwordx4 v0, s[42:43]
	ds_read_b128 v[202:205], v132 offset:19456
	ds_read_b128 v[206:209], v132 offset:20480
	ds_read_b128 v[210:213], v132 offset:21504
	ds_read_b128 v[214:217], v132 offset:22528
	ds_read_b128 v[218:221], v132 offset:23552
	s_waitcnt vmcnt(6)
	s_waitcnt lgkmcnt(0)
	s_barrier
	s_setprio 1
	s_waitcnt lgkmcnt(0)
	v_mfma_f32_16x16x32_bf16 v[64:67], v[146:149], v[190:193], v[64:67]
	v_mfma_f32_16x16x32_bf16 v[60:63], v[154:157], v[190:193], v[60:63]
	v_mfma_f32_16x16x32_bf16 v[48:51], v[146:149], v[198:201], v[48:51]
	v_mfma_f32_16x16x32_bf16 v[44:47], v[154:157], v[198:201], v[44:47]
	v_mfma_f32_16x16x32_bf16 v[32:35], v[146:149], v[206:209], v[32:35]
	v_mfma_f32_16x16x32_bf16 v[28:31], v[154:157], v[206:209], v[28:31]
	v_mfma_f32_16x16x32_bf16 v[16:19], v[146:149], v[214:217], v[16:19]
	v_mfma_f32_16x16x32_bf16 v[12:15], v[154:157], v[214:217], v[12:15]
	v_mfma_f32_16x16x32_bf16 v[64:67], v[150:153], v[194:197], v[64:67]
	v_mfma_f32_16x16x32_bf16 v[60:63], v[158:161], v[194:197], v[60:63]
	v_mfma_f32_16x16x32_bf16 v[48:51], v[150:153], v[202:205], v[48:51]
	v_mfma_f32_16x16x32_bf16 v[44:47], v[158:161], v[202:205], v[44:47]
	v_mfma_f32_16x16x32_bf16 v[32:35], v[150:153], v[210:213], v[32:35]
	v_mfma_f32_16x16x32_bf16 v[28:31], v[158:161], v[210:213], v[28:31]
	v_mfma_f32_16x16x32_bf16 v[16:19], v[150:153], v[218:221], v[16:19]
	v_mfma_f32_16x16x32_bf16 v[12:15], v[158:161], v[218:221], v[12:15]
	s_setprio 0
	s_setprio 1
	v_mfma_f32_16x16x32_bf16 v[56:59], v[162:165], v[190:193], v[56:59]
	v_mfma_f32_16x16x32_bf16 v[52:55], v[170:173], v[190:193], v[52:55]
	v_mfma_f32_16x16x32_bf16 v[40:43], v[162:165], v[198:201], v[40:43]
	v_mfma_f32_16x16x32_bf16 v[36:39], v[170:173], v[198:201], v[36:39]
	v_mfma_f32_16x16x32_bf16 v[24:27], v[162:165], v[206:209], v[24:27]
	v_mfma_f32_16x16x32_bf16 v[20:23], v[170:173], v[206:209], v[20:23]
	v_mfma_f32_16x16x32_bf16 v[8:11], v[162:165], v[214:217], v[8:11]
	v_mfma_f32_16x16x32_bf16 v[4:7], v[170:173], v[214:217], v[4:7]
	v_mfma_f32_16x16x32_bf16 v[56:59], v[166:169], v[194:197], v[56:59]
	v_mfma_f32_16x16x32_bf16 v[52:55], v[186:189], v[194:197], v[52:55]
	v_mfma_f32_16x16x32_bf16 v[40:43], v[166:169], v[202:205], v[40:43]
	v_mfma_f32_16x16x32_bf16 v[36:39], v[186:189], v[202:205], v[36:39]
	v_mfma_f32_16x16x32_bf16 v[24:27], v[166:169], v[210:213], v[24:27]
	v_mfma_f32_16x16x32_bf16 v[20:23], v[186:189], v[210:213], v[20:23]
	v_mfma_f32_16x16x32_bf16 v[8:11], v[166:169], v[218:221], v[8:11]
	v_mfma_f32_16x16x32_bf16 v[4:7], v[186:189], v[218:221], v[4:7]
	s_setprio 0
	s_barrier
	s_mov_b32 m0, s56
	s_add_u32 s42, s50, 0x40000
	s_addc_u32 s43, s51, 0
	global_load_lds_dwordx4 v144, s[50:51]
	s_mov_b32 m0, s57
	ds_read_b128 v[146:149], v240 offset:32768
	global_load_lds_dwordx4 v140, s[50:51]
	ds_read_b128 v[150:153], v240 offset:33792
	ds_read_b128 v[154:157], v240 offset:34816
	ds_read_b128 v[158:161], v240 offset:35840
	ds_read_b128 v[162:165], v240 offset:49152
	ds_read_b128 v[166:169], v240 offset:50176
	ds_read_b128 v[170:173], v240 offset:51200
	ds_read_b128 v[186:189], v240 offset:52224
	s_mov_b32 m0, s58
	ds_read_b128 v[190:193], v132 offset:32768
	global_load_lds_dwordx4 v144, s[42:43]
	s_mov_b32 m0, s59
	ds_read_b128 v[194:197], v132 offset:33792
	global_load_lds_dwordx4 v140, s[42:43]
	ds_read_b128 v[198:201], v132 offset:34816
	ds_read_b128 v[202:205], v132 offset:35840
	ds_read_b128 v[206:209], v132 offset:36864
	ds_read_b128 v[210:213], v132 offset:37888
	ds_read_b128 v[214:217], v132 offset:38912
	ds_read_b128 v[218:221], v132 offset:39936
	s_waitcnt vmcnt(8)
	s_waitcnt lgkmcnt(8)
	s_barrier
	s_setprio 1
	s_waitcnt lgkmcnt(0)
	v_mfma_f32_16x16x32_bf16 v[128:131], v[146:149], v[190:193], v[128:131]
	v_mfma_f32_16x16x32_bf16 v[124:127], v[154:157], v[190:193], v[124:127]
	v_mfma_f32_16x16x32_bf16 v[112:115], v[146:149], v[198:201], v[112:115]
	v_mfma_f32_16x16x32_bf16 v[108:111], v[154:157], v[198:201], v[108:111]
	v_mfma_f32_16x16x32_bf16 v[96:99], v[146:149], v[206:209], v[96:99]
	v_mfma_f32_16x16x32_bf16 v[92:95], v[154:157], v[206:209], v[92:95]
	v_mfma_f32_16x16x32_bf16 v[80:83], v[146:149], v[214:217], v[80:83]
	v_mfma_f32_16x16x32_bf16 v[76:79], v[154:157], v[214:217], v[76:79]
	v_mfma_f32_16x16x32_bf16 v[128:131], v[150:153], v[194:197], v[128:131]
	v_mfma_f32_16x16x32_bf16 v[124:127], v[158:161], v[194:197], v[124:127]
	v_mfma_f32_16x16x32_bf16 v[112:115], v[150:153], v[202:205], v[112:115]
	v_mfma_f32_16x16x32_bf16 v[108:111], v[158:161], v[202:205], v[108:111]
	v_mfma_f32_16x16x32_bf16 v[96:99], v[150:153], v[210:213], v[96:99]
	v_mfma_f32_16x16x32_bf16 v[92:95], v[158:161], v[210:213], v[92:95]
	v_mfma_f32_16x16x32_bf16 v[80:83], v[150:153], v[218:221], v[80:83]
	v_mfma_f32_16x16x32_bf16 v[76:79], v[158:161], v[218:221], v[76:79]
	s_setprio 0
	s_setprio 1
	v_mfma_f32_16x16x32_bf16 v[120:123], v[162:165], v[190:193], v[120:123]
	v_mfma_f32_16x16x32_bf16 v[116:119], v[170:173], v[190:193], v[116:119]
	v_mfma_f32_16x16x32_bf16 v[104:107], v[162:165], v[198:201], v[104:107]
	v_mfma_f32_16x16x32_bf16 v[100:103], v[170:173], v[198:201], v[100:103]
	v_mfma_f32_16x16x32_bf16 v[88:91], v[162:165], v[206:209], v[88:91]
	v_mfma_f32_16x16x32_bf16 v[84:87], v[170:173], v[206:209], v[84:87]
	v_mfma_f32_16x16x32_bf16 v[72:75], v[162:165], v[214:217], v[72:75]
	v_mfma_f32_16x16x32_bf16 v[68:71], v[170:173], v[214:217], v[68:71]
	v_mfma_f32_16x16x32_bf16 v[120:123], v[166:169], v[194:197], v[120:123]
	v_mfma_f32_16x16x32_bf16 v[116:119], v[186:189], v[194:197], v[116:119]
	v_mfma_f32_16x16x32_bf16 v[104:107], v[166:169], v[202:205], v[104:107]
	v_mfma_f32_16x16x32_bf16 v[100:103], v[186:189], v[202:205], v[100:103]
	v_mfma_f32_16x16x32_bf16 v[88:91], v[166:169], v[210:213], v[88:91]
	v_mfma_f32_16x16x32_bf16 v[84:87], v[186:189], v[210:213], v[84:87]
	v_mfma_f32_16x16x32_bf16 v[72:75], v[166:169], v[218:221], v[72:75]
	v_mfma_f32_16x16x32_bf16 v[68:71], v[186:189], v[218:221], v[68:71]
	s_setprio 0
	s_barrier
	s_add_u32 s42, s48, 0x80
	s_addc_u32 s43, s49, 0
	s_add_i32 m0, s69, 0x18000
	s_add_u32 s46, s48, 0x40080
	s_addc_u32 s47, s49, 0
	global_load_lds_dwordx4 v142, s[42:43]
	s_add_i32 m0, s69, 0x1a000
	ds_read_b128 v[190:193], v132 offset:49152
	global_load_lds_dwordx4 v0, s[42:43]
	s_add_i32 m0, s69, 0x1c000
	ds_read_b128 v[194:197], v132 offset:50176
	global_load_lds_dwordx4 v142, s[46:47]
	s_add_i32 m0, s69, 0x1e000
	ds_read_b128 v[198:201], v132 offset:51200
	global_load_lds_dwordx4 v0, s[46:47]
	ds_read_b128 v[202:205], v132 offset:52224
	ds_read_b128 v[206:209], v132 offset:53248
	ds_read_b128 v[210:213], v132 offset:54272
	ds_read_b128 v[214:217], v132 offset:55296
	ds_read_b128 v[218:221], v132 offset:56320
	s_waitcnt vmcnt(6)
	s_waitcnt lgkmcnt(0)
	s_barrier
	s_setprio 1
	s_waitcnt lgkmcnt(0)
	v_mfma_f32_16x16x32_bf16 v[64:67], v[146:149], v[190:193], v[64:67]
	v_mfma_f32_16x16x32_bf16 v[60:63], v[154:157], v[190:193], v[60:63]
	v_mfma_f32_16x16x32_bf16 v[48:51], v[146:149], v[198:201], v[48:51]
	v_mfma_f32_16x16x32_bf16 v[44:47], v[154:157], v[198:201], v[44:47]
	v_mfma_f32_16x16x32_bf16 v[32:35], v[146:149], v[206:209], v[32:35]
	v_mfma_f32_16x16x32_bf16 v[28:31], v[154:157], v[206:209], v[28:31]
	v_mfma_f32_16x16x32_bf16 v[16:19], v[146:149], v[214:217], v[16:19]
	v_mfma_f32_16x16x32_bf16 v[12:15], v[154:157], v[214:217], v[12:15]
	v_mfma_f32_16x16x32_bf16 v[64:67], v[150:153], v[194:197], v[64:67]
	v_mfma_f32_16x16x32_bf16 v[60:63], v[158:161], v[194:197], v[60:63]
	v_mfma_f32_16x16x32_bf16 v[48:51], v[150:153], v[202:205], v[48:51]
	v_mfma_f32_16x16x32_bf16 v[44:47], v[158:161], v[202:205], v[44:47]
	v_mfma_f32_16x16x32_bf16 v[32:35], v[150:153], v[210:213], v[32:35]
	v_mfma_f32_16x16x32_bf16 v[28:31], v[158:161], v[210:213], v[28:31]
	v_mfma_f32_16x16x32_bf16 v[16:19], v[150:153], v[218:221], v[16:19]
	v_mfma_f32_16x16x32_bf16 v[12:15], v[158:161], v[218:221], v[12:15]
	s_setprio 0
	s_setprio 1
	v_mfma_f32_16x16x32_bf16 v[56:59], v[162:165], v[190:193], v[56:59]
	v_mfma_f32_16x16x32_bf16 v[52:55], v[170:173], v[190:193], v[52:55]
	v_mfma_f32_16x16x32_bf16 v[40:43], v[162:165], v[198:201], v[40:43]
	v_mfma_f32_16x16x32_bf16 v[36:39], v[170:173], v[198:201], v[36:39]
	v_mfma_f32_16x16x32_bf16 v[24:27], v[162:165], v[206:209], v[24:27]
	v_mfma_f32_16x16x32_bf16 v[20:23], v[170:173], v[206:209], v[20:23]
	v_mfma_f32_16x16x32_bf16 v[8:11], v[162:165], v[214:217], v[8:11]
	v_mfma_f32_16x16x32_bf16 v[4:7], v[170:173], v[214:217], v[4:7]
	v_mfma_f32_16x16x32_bf16 v[56:59], v[166:169], v[194:197], v[56:59]
	v_mfma_f32_16x16x32_bf16 v[52:55], v[186:189], v[194:197], v[52:55]
	v_mfma_f32_16x16x32_bf16 v[40:43], v[166:169], v[202:205], v[40:43]
	v_mfma_f32_16x16x32_bf16 v[36:39], v[186:189], v[202:205], v[36:39]
	v_mfma_f32_16x16x32_bf16 v[24:27], v[166:169], v[210:213], v[24:27]
	v_mfma_f32_16x16x32_bf16 v[20:23], v[186:189], v[210:213], v[20:23]
	v_mfma_f32_16x16x32_bf16 v[8:11], v[166:169], v[218:221], v[8:11]
	v_mfma_f32_16x16x32_bf16 v[4:7], v[186:189], v[218:221], v[4:7]
	s_setprio 0
	s_barrier
	s_add_i32 s63, s63, 2
	s_add_u32 s28, s28, 0x100
	s_addc_u32 s29, s29, 0
	s_cmp_gt_u32 s63, 13
	s_mov_b64 s[42:43], s[44:45]
	s_cbranch_scc0 .LBB0_500
	s_andn2_b64 vcc, s[14:15], s[40:41]
	s_and_b64 vcc, exec, vcc
	s_cbranch_vccz .LBB0_503
	s_barrier
.LBB0_503:
	v_mov_b32_e32 v139, v174
	s_lshl_b32 s5, s9, 8
	s_add_i32 s5, s5, s70
	v_and_or_b32 v138, v139, 15, s5
	s_lshl_b32 s5, s8, 7
	v_ashrrev_i32_e32 v139, 1, v139
	s_or_b32 s5, s5, s71
	v_and_b32_e32 v139, -8, v139
	v_add_u32_e32 v148, s5, v139
	v_ashrrev_i32_e32 v149, 31, v148
	v_mov_b64_e32 v[146:147], s[0:1]
	v_ashrrev_i32_e32 v139, 31, v138
	v_mad_i64_i32 v[150:151], s[8:9], v138, s73, v[146:147]
	v_lshlrev_b64 v[148:149], 1, v[148:149]
	v_lshl_add_u64 v[152:153], v[150:151], 0, v[148:149]
	v_lshl_add_u64 v[150:151], v[138:139], 2, s[2:3]
	global_load_dword v206, v[150:151], off
	global_load_dword v208, v[150:151], off offset:64
	global_load_dword v210, v[150:151], off offset:128
	global_load_dword v212, v[150:151], off offset:192
	global_load_dword v214, v[150:151], off offset:512
	global_load_dword v216, v[150:151], off offset:576
	global_load_dword v218, v[150:151], off offset:640
	global_load_dword v220, v[150:151], off offset:704
	s_mov_b64 s[42:43], -1
	s_andn2_b64 vcc, exec, s[40:41]
	v_mov_b32_e32 v154, 0xbfb8aa3b
	v_mov_b32_e32 v155, 0xbfb8aa3b
	v_mov_b32_e32 v156, 1.0
	v_mov_b32_e32 v157, 1.0
	v_mov_b32_e32 v159, 0
	s_waitcnt vmcnt(0)
	v_pk_mul_f32 v[128:129], v[128:129], v[206:207] op_sel_hi:[1,0]
	v_pk_mul_f32 v[130:131], v[130:131], v[206:207] op_sel_hi:[1,0]
	v_pk_mul_f32 v[124:125], v[124:125], v[206:207] op_sel_hi:[1,0]
	v_pk_mul_f32 v[126:127], v[126:127], v[206:207] op_sel_hi:[1,0]
	v_pk_mul_f32 v[162:163], v[128:129], v[154:155]
	v_pk_mul_f32 v[164:165], v[130:131], v[154:155]
	v_pk_mul_f32 v[166:167], v[124:125], v[154:155]
	v_pk_mul_f32 v[168:169], v[126:127], v[154:155]
	v_exp_f32_e32 v162, v162
	v_exp_f32_e32 v163, v163
	v_exp_f32_e32 v164, v164
	v_exp_f32_e32 v165, v165
	v_exp_f32_e32 v166, v166
	v_exp_f32_e32 v167, v167
	v_exp_f32_e32 v168, v168
	v_exp_f32_e32 v169, v169
	v_pk_mul_f32 v[120:121], v[120:121], v[206:207] op_sel_hi:[1,0]
	v_pk_mul_f32 v[122:123], v[122:123], v[206:207] op_sel_hi:[1,0]
	v_pk_mul_f32 v[116:117], v[116:117], v[206:207] op_sel_hi:[1,0]
	v_pk_mul_f32 v[118:119], v[118:119], v[206:207] op_sel_hi:[1,0]
	v_pk_add_f32 v[162:163], v[162:163], v[156:157]
	v_pk_add_f32 v[164:165], v[164:165], v[156:157]
	v_pk_add_f32 v[166:167], v[166:167], v[156:157]
	v_pk_add_f32 v[168:169], v[168:169], v[156:157]
	v_rcp_f32_e32 v162, v162
	v_rcp_f32_e32 v163, v163
	v_rcp_f32_e32 v164, v164
	v_rcp_f32_e32 v165, v165
	v_rcp_f32_e32 v166, v166
	v_rcp_f32_e32 v167, v167
	v_rcp_f32_e32 v168, v168
	v_rcp_f32_e32 v169, v169
	v_pk_mul_f32 v[128:129], v[128:129], v[120:121]
	v_pk_mul_f32 v[130:131], v[130:131], v[122:123]
	v_pk_mul_f32 v[124:125], v[124:125], v[116:117]
	v_pk_mul_f32 v[126:127], v[126:127], v[118:119]
	v_pk_mul_f32 v[128:129], v[128:129], v[162:163]
	v_pk_mul_f32 v[130:131], v[130:131], v[164:165]
	v_pk_mul_f32 v[124:125], v[124:125], v[166:167]
	v_pk_mul_f32 v[126:127], v[126:127], v[168:169]
	v_cvt_pk_bf16_f32 v170, v128, v129
	v_cvt_pk_bf16_f32 v171, v130, v131
	v_cvt_pk_bf16_f32 v172, v124, v125
	v_cvt_pk_bf16_f32 v173, v126, v127
	global_store_dwordx4 v[152:153], v[170:173], off
	v_pk_mul_f32 v[112:113], v[112:113], v[208:209] op_sel_hi:[1,0]
	v_pk_mul_f32 v[114:115], v[114:115], v[208:209] op_sel_hi:[1,0]
	v_pk_mul_f32 v[108:109], v[108:109], v[208:209] op_sel_hi:[1,0]
	v_pk_mul_f32 v[110:111], v[110:111], v[208:209] op_sel_hi:[1,0]
	v_pk_mul_f32 v[162:163], v[112:113], v[154:155]
	v_pk_mul_f32 v[164:165], v[114:115], v[154:155]
	v_pk_mul_f32 v[166:167], v[108:109], v[154:155]
	v_pk_mul_f32 v[168:169], v[110:111], v[154:155]
	v_exp_f32_e32 v162, v162
	v_exp_f32_e32 v163, v163
	v_exp_f32_e32 v164, v164
	v_exp_f32_e32 v165, v165
	v_exp_f32_e32 v166, v166
	v_exp_f32_e32 v167, v167
	v_exp_f32_e32 v168, v168
	v_exp_f32_e32 v169, v169
	v_pk_mul_f32 v[104:105], v[104:105], v[208:209] op_sel_hi:[1,0]
	v_pk_mul_f32 v[106:107], v[106:107], v[208:209] op_sel_hi:[1,0]
	v_pk_mul_f32 v[100:101], v[100:101], v[208:209] op_sel_hi:[1,0]
	v_pk_mul_f32 v[102:103], v[102:103], v[208:209] op_sel_hi:[1,0]
	v_pk_add_f32 v[162:163], v[162:163], v[156:157]
	v_pk_add_f32 v[164:165], v[164:165], v[156:157]
	v_pk_add_f32 v[166:167], v[166:167], v[156:157]
	v_pk_add_f32 v[168:169], v[168:169], v[156:157]
	v_rcp_f32_e32 v162, v162
	v_rcp_f32_e32 v163, v163
	v_rcp_f32_e32 v164, v164
	v_rcp_f32_e32 v165, v165
	v_rcp_f32_e32 v166, v166
	v_rcp_f32_e32 v167, v167
	v_rcp_f32_e32 v168, v168
	v_rcp_f32_e32 v169, v169
	v_pk_mul_f32 v[112:113], v[112:113], v[104:105]
	v_pk_mul_f32 v[114:115], v[114:115], v[106:107]
	v_pk_mul_f32 v[108:109], v[108:109], v[100:101]
	v_pk_mul_f32 v[110:111], v[110:111], v[102:103]
	v_pk_mul_f32 v[112:113], v[112:113], v[162:163]
	v_pk_mul_f32 v[114:115], v[114:115], v[164:165]
	v_pk_mul_f32 v[108:109], v[108:109], v[166:167]
	v_pk_mul_f32 v[110:111], v[110:111], v[168:169]
	v_cvt_pk_bf16_f32 v186, v112, v113
	v_cvt_pk_bf16_f32 v187, v114, v115
	v_cvt_pk_bf16_f32 v188, v108, v109
	v_cvt_pk_bf16_f32 v189, v110, v111
	v_mov_b32_e32 v158, 0x16000
	v_lshl_add_u64 v[160:161], v[152:153], 0, v[158:159]
	global_store_dwordx4 v[160:161], v[186:189], off
	v_pk_mul_f32 v[96:97], v[96:97], v[210:211] op_sel_hi:[1,0]
	v_pk_mul_f32 v[98:99], v[98:99], v[210:211] op_sel_hi:[1,0]
	v_pk_mul_f32 v[92:93], v[92:93], v[210:211] op_sel_hi:[1,0]
	v_pk_mul_f32 v[94:95], v[94:95], v[210:211] op_sel_hi:[1,0]
	v_pk_mul_f32 v[162:163], v[96:97], v[154:155]
	v_pk_mul_f32 v[164:165], v[98:99], v[154:155]
	v_pk_mul_f32 v[166:167], v[92:93], v[154:155]
	v_pk_mul_f32 v[168:169], v[94:95], v[154:155]
	v_exp_f32_e32 v162, v162
	v_exp_f32_e32 v163, v163
	v_exp_f32_e32 v164, v164
	v_exp_f32_e32 v165, v165
	v_exp_f32_e32 v166, v166
	v_exp_f32_e32 v167, v167
	v_exp_f32_e32 v168, v168
	v_exp_f32_e32 v169, v169
	v_pk_mul_f32 v[88:89], v[88:89], v[210:211] op_sel_hi:[1,0]
	v_pk_mul_f32 v[90:91], v[90:91], v[210:211] op_sel_hi:[1,0]
	v_pk_mul_f32 v[84:85], v[84:85], v[210:211] op_sel_hi:[1,0]
	v_pk_mul_f32 v[86:87], v[86:87], v[210:211] op_sel_hi:[1,0]
	v_pk_add_f32 v[162:163], v[162:163], v[156:157]
	v_pk_add_f32 v[164:165], v[164:165], v[156:157]
	v_pk_add_f32 v[166:167], v[166:167], v[156:157]
	v_pk_add_f32 v[168:169], v[168:169], v[156:157]
	v_rcp_f32_e32 v162, v162
	v_rcp_f32_e32 v163, v163
	v_rcp_f32_e32 v164, v164
	v_rcp_f32_e32 v165, v165
	v_rcp_f32_e32 v166, v166
	v_rcp_f32_e32 v167, v167
	v_rcp_f32_e32 v168, v168
	v_rcp_f32_e32 v169, v169
	v_pk_mul_f32 v[96:97], v[96:97], v[88:89]
	v_pk_mul_f32 v[98:99], v[98:99], v[90:91]
	v_pk_mul_f32 v[92:93], v[92:93], v[84:85]
	v_pk_mul_f32 v[94:95], v[94:95], v[86:87]
	v_pk_mul_f32 v[96:97], v[96:97], v[162:163]
	v_pk_mul_f32 v[98:99], v[98:99], v[164:165]
	v_pk_mul_f32 v[92:93], v[92:93], v[166:167]
	v_pk_mul_f32 v[94:95], v[94:95], v[168:169]
	v_cvt_pk_bf16_f32 v170, v96, v97
	v_cvt_pk_bf16_f32 v171, v98, v99
	v_cvt_pk_bf16_f32 v172, v92, v93
	v_cvt_pk_bf16_f32 v173, v94, v95
	v_mov_b32_e32 v158, 0x2c000
	v_lshl_add_u64 v[160:161], v[152:153], 0, v[158:159]
	global_store_dwordx4 v[160:161], v[170:173], off
	v_pk_mul_f32 v[80:81], v[80:81], v[212:213] op_sel_hi:[1,0]
	v_pk_mul_f32 v[82:83], v[82:83], v[212:213] op_sel_hi:[1,0]
	v_pk_mul_f32 v[76:77], v[76:77], v[212:213] op_sel_hi:[1,0]
	v_pk_mul_f32 v[78:79], v[78:79], v[212:213] op_sel_hi:[1,0]
	v_pk_mul_f32 v[162:163], v[80:81], v[154:155]
	v_pk_mul_f32 v[164:165], v[82:83], v[154:155]
	v_pk_mul_f32 v[166:167], v[76:77], v[154:155]
	v_pk_mul_f32 v[168:169], v[78:79], v[154:155]
	v_exp_f32_e32 v162, v162
	v_exp_f32_e32 v163, v163
	v_exp_f32_e32 v164, v164
	v_exp_f32_e32 v165, v165
	v_exp_f32_e32 v166, v166
	v_exp_f32_e32 v167, v167
	v_exp_f32_e32 v168, v168
	v_exp_f32_e32 v169, v169
	v_pk_mul_f32 v[72:73], v[72:73], v[212:213] op_sel_hi:[1,0]
	v_pk_mul_f32 v[74:75], v[74:75], v[212:213] op_sel_hi:[1,0]
	v_pk_mul_f32 v[68:69], v[68:69], v[212:213] op_sel_hi:[1,0]
	v_pk_mul_f32 v[70:71], v[70:71], v[212:213] op_sel_hi:[1,0]
	v_pk_add_f32 v[162:163], v[162:163], v[156:157]
	v_pk_add_f32 v[164:165], v[164:165], v[156:157]
	v_pk_add_f32 v[166:167], v[166:167], v[156:157]
	v_pk_add_f32 v[168:169], v[168:169], v[156:157]
	v_rcp_f32_e32 v162, v162
	v_rcp_f32_e32 v163, v163
	v_rcp_f32_e32 v164, v164
	v_rcp_f32_e32 v165, v165
	v_rcp_f32_e32 v166, v166
	v_rcp_f32_e32 v167, v167
	v_rcp_f32_e32 v168, v168
	v_rcp_f32_e32 v169, v169
	v_pk_mul_f32 v[80:81], v[80:81], v[72:73]
	v_pk_mul_f32 v[82:83], v[82:83], v[74:75]
	v_pk_mul_f32 v[76:77], v[76:77], v[68:69]
	v_pk_mul_f32 v[78:79], v[78:79], v[70:71]
	v_pk_mul_f32 v[80:81], v[80:81], v[162:163]
	v_pk_mul_f32 v[82:83], v[82:83], v[164:165]
	v_pk_mul_f32 v[76:77], v[76:77], v[166:167]
	v_pk_mul_f32 v[78:79], v[78:79], v[168:169]
	v_cvt_pk_bf16_f32 v186, v80, v81
	v_cvt_pk_bf16_f32 v187, v82, v83
	v_cvt_pk_bf16_f32 v188, v76, v77
	v_cvt_pk_bf16_f32 v189, v78, v79
	v_mov_b32_e32 v158, 0x42000
	v_lshl_add_u64 v[160:161], v[152:153], 0, v[158:159]
	global_store_dwordx4 v[160:161], v[186:189], off
	v_pk_mul_f32 v[64:65], v[64:65], v[214:215] op_sel_hi:[1,0]
	v_pk_mul_f32 v[66:67], v[66:67], v[214:215] op_sel_hi:[1,0]
	v_pk_mul_f32 v[60:61], v[60:61], v[214:215] op_sel_hi:[1,0]
	v_pk_mul_f32 v[62:63], v[62:63], v[214:215] op_sel_hi:[1,0]
	v_pk_mul_f32 v[162:163], v[64:65], v[154:155]
	v_pk_mul_f32 v[164:165], v[66:67], v[154:155]
	v_pk_mul_f32 v[166:167], v[60:61], v[154:155]
	v_pk_mul_f32 v[168:169], v[62:63], v[154:155]
	v_exp_f32_e32 v162, v162
	v_exp_f32_e32 v163, v163
	v_exp_f32_e32 v164, v164
	v_exp_f32_e32 v165, v165
	v_exp_f32_e32 v166, v166
	v_exp_f32_e32 v167, v167
	v_exp_f32_e32 v168, v168
	v_exp_f32_e32 v169, v169
	v_pk_mul_f32 v[56:57], v[56:57], v[214:215] op_sel_hi:[1,0]
	v_pk_mul_f32 v[58:59], v[58:59], v[214:215] op_sel_hi:[1,0]
	v_pk_mul_f32 v[52:53], v[52:53], v[214:215] op_sel_hi:[1,0]
	v_pk_mul_f32 v[54:55], v[54:55], v[214:215] op_sel_hi:[1,0]
	v_pk_add_f32 v[162:163], v[162:163], v[156:157]
	v_pk_add_f32 v[164:165], v[164:165], v[156:157]
	v_pk_add_f32 v[166:167], v[166:167], v[156:157]
	v_pk_add_f32 v[168:169], v[168:169], v[156:157]
	v_rcp_f32_e32 v162, v162
	v_rcp_f32_e32 v163, v163
	v_rcp_f32_e32 v164, v164
	v_rcp_f32_e32 v165, v165
	v_rcp_f32_e32 v166, v166
	v_rcp_f32_e32 v167, v167
	v_rcp_f32_e32 v168, v168
	v_rcp_f32_e32 v169, v169
	v_pk_mul_f32 v[64:65], v[64:65], v[56:57]
	v_pk_mul_f32 v[66:67], v[66:67], v[58:59]
	v_pk_mul_f32 v[60:61], v[60:61], v[52:53]
	v_pk_mul_f32 v[62:63], v[62:63], v[54:55]
	v_pk_mul_f32 v[64:65], v[64:65], v[162:163]
	v_pk_mul_f32 v[66:67], v[66:67], v[164:165]
	v_pk_mul_f32 v[60:61], v[60:61], v[166:167]
	v_pk_mul_f32 v[62:63], v[62:63], v[168:169]
	v_cvt_pk_bf16_f32 v170, v64, v65
	v_cvt_pk_bf16_f32 v171, v66, v67
	v_cvt_pk_bf16_f32 v172, v60, v61
	v_cvt_pk_bf16_f32 v173, v62, v63
	v_mov_b32_e32 v158, 0xb0000
	v_lshl_add_u64 v[160:161], v[152:153], 0, v[158:159]
	global_store_dwordx4 v[160:161], v[170:173], off
	v_pk_mul_f32 v[48:49], v[48:49], v[216:217] op_sel_hi:[1,0]
	v_pk_mul_f32 v[50:51], v[50:51], v[216:217] op_sel_hi:[1,0]
	v_pk_mul_f32 v[44:45], v[44:45], v[216:217] op_sel_hi:[1,0]
	v_pk_mul_f32 v[46:47], v[46:47], v[216:217] op_sel_hi:[1,0]
	v_pk_mul_f32 v[162:163], v[48:49], v[154:155]
	v_pk_mul_f32 v[164:165], v[50:51], v[154:155]
	v_pk_mul_f32 v[166:167], v[44:45], v[154:155]
	v_pk_mul_f32 v[168:169], v[46:47], v[154:155]
	v_exp_f32_e32 v162, v162
	v_exp_f32_e32 v163, v163
	v_exp_f32_e32 v164, v164
	v_exp_f32_e32 v165, v165
	v_exp_f32_e32 v166, v166
	v_exp_f32_e32 v167, v167
	v_exp_f32_e32 v168, v168
	v_exp_f32_e32 v169, v169
	v_pk_mul_f32 v[40:41], v[40:41], v[216:217] op_sel_hi:[1,0]
	v_pk_mul_f32 v[42:43], v[42:43], v[216:217] op_sel_hi:[1,0]
	v_pk_mul_f32 v[36:37], v[36:37], v[216:217] op_sel_hi:[1,0]
	v_pk_mul_f32 v[38:39], v[38:39], v[216:217] op_sel_hi:[1,0]
	v_pk_add_f32 v[162:163], v[162:163], v[156:157]
	v_pk_add_f32 v[164:165], v[164:165], v[156:157]
	v_pk_add_f32 v[166:167], v[166:167], v[156:157]
	v_pk_add_f32 v[168:169], v[168:169], v[156:157]
	v_rcp_f32_e32 v162, v162
	v_rcp_f32_e32 v163, v163
	v_rcp_f32_e32 v164, v164
	v_rcp_f32_e32 v165, v165
	v_rcp_f32_e32 v166, v166
	v_rcp_f32_e32 v167, v167
	v_rcp_f32_e32 v168, v168
	v_rcp_f32_e32 v169, v169
	v_pk_mul_f32 v[48:49], v[48:49], v[40:41]
	v_pk_mul_f32 v[50:51], v[50:51], v[42:43]
	v_pk_mul_f32 v[44:45], v[44:45], v[36:37]
	v_pk_mul_f32 v[46:47], v[46:47], v[38:39]
	v_pk_mul_f32 v[48:49], v[48:49], v[162:163]
	v_pk_mul_f32 v[50:51], v[50:51], v[164:165]
	v_pk_mul_f32 v[44:45], v[44:45], v[166:167]
	v_pk_mul_f32 v[46:47], v[46:47], v[168:169]
	v_cvt_pk_bf16_f32 v186, v48, v49
	v_cvt_pk_bf16_f32 v187, v50, v51
	v_cvt_pk_bf16_f32 v188, v44, v45
	v_cvt_pk_bf16_f32 v189, v46, v47
	v_mov_b32_e32 v158, 0xc6000
	v_lshl_add_u64 v[160:161], v[152:153], 0, v[158:159]
	global_store_dwordx4 v[160:161], v[186:189], off
	v_pk_mul_f32 v[32:33], v[32:33], v[218:219] op_sel_hi:[1,0]
	v_pk_mul_f32 v[34:35], v[34:35], v[218:219] op_sel_hi:[1,0]
	v_pk_mul_f32 v[28:29], v[28:29], v[218:219] op_sel_hi:[1,0]
	v_pk_mul_f32 v[30:31], v[30:31], v[218:219] op_sel_hi:[1,0]
	v_pk_mul_f32 v[162:163], v[32:33], v[154:155]
	v_pk_mul_f32 v[164:165], v[34:35], v[154:155]
	v_pk_mul_f32 v[166:167], v[28:29], v[154:155]
	v_pk_mul_f32 v[168:169], v[30:31], v[154:155]
	v_exp_f32_e32 v162, v162
	v_exp_f32_e32 v163, v163
	v_exp_f32_e32 v164, v164
	v_exp_f32_e32 v165, v165
	v_exp_f32_e32 v166, v166
	v_exp_f32_e32 v167, v167
	v_exp_f32_e32 v168, v168
	v_exp_f32_e32 v169, v169
	v_pk_mul_f32 v[24:25], v[24:25], v[218:219] op_sel_hi:[1,0]
	v_pk_mul_f32 v[26:27], v[26:27], v[218:219] op_sel_hi:[1,0]
	v_pk_mul_f32 v[20:21], v[20:21], v[218:219] op_sel_hi:[1,0]
	v_pk_mul_f32 v[22:23], v[22:23], v[218:219] op_sel_hi:[1,0]
	v_pk_add_f32 v[162:163], v[162:163], v[156:157]
	v_pk_add_f32 v[164:165], v[164:165], v[156:157]
	v_pk_add_f32 v[166:167], v[166:167], v[156:157]
	v_pk_add_f32 v[168:169], v[168:169], v[156:157]
	v_rcp_f32_e32 v162, v162
	v_rcp_f32_e32 v163, v163
	v_rcp_f32_e32 v164, v164
	v_rcp_f32_e32 v165, v165
	v_rcp_f32_e32 v166, v166
	v_rcp_f32_e32 v167, v167
	v_rcp_f32_e32 v168, v168
	v_rcp_f32_e32 v169, v169
	v_pk_mul_f32 v[32:33], v[32:33], v[24:25]
	v_pk_mul_f32 v[34:35], v[34:35], v[26:27]
	v_pk_mul_f32 v[28:29], v[28:29], v[20:21]
	v_pk_mul_f32 v[30:31], v[30:31], v[22:23]
	v_pk_mul_f32 v[32:33], v[32:33], v[162:163]
	v_pk_mul_f32 v[34:35], v[34:35], v[164:165]
	v_pk_mul_f32 v[28:29], v[28:29], v[166:167]
	v_pk_mul_f32 v[30:31], v[30:31], v[168:169]
	v_cvt_pk_bf16_f32 v170, v32, v33
	v_cvt_pk_bf16_f32 v171, v34, v35
	v_cvt_pk_bf16_f32 v172, v28, v29
	v_cvt_pk_bf16_f32 v173, v30, v31
	v_mov_b32_e32 v158, 0xdc000
	v_lshl_add_u64 v[160:161], v[152:153], 0, v[158:159]
	global_store_dwordx4 v[160:161], v[170:173], off
	v_pk_mul_f32 v[16:17], v[16:17], v[220:221] op_sel_hi:[1,0]
	v_pk_mul_f32 v[18:19], v[18:19], v[220:221] op_sel_hi:[1,0]
	v_pk_mul_f32 v[12:13], v[12:13], v[220:221] op_sel_hi:[1,0]
	v_pk_mul_f32 v[14:15], v[14:15], v[220:221] op_sel_hi:[1,0]
	v_pk_mul_f32 v[162:163], v[16:17], v[154:155]
	v_pk_mul_f32 v[164:165], v[18:19], v[154:155]
	v_pk_mul_f32 v[166:167], v[12:13], v[154:155]
	v_pk_mul_f32 v[168:169], v[14:15], v[154:155]
	v_exp_f32_e32 v162, v162
	v_exp_f32_e32 v163, v163
	v_exp_f32_e32 v164, v164
	v_exp_f32_e32 v165, v165
	v_exp_f32_e32 v166, v166
	v_exp_f32_e32 v167, v167
	v_exp_f32_e32 v168, v168
	v_exp_f32_e32 v169, v169
	v_pk_mul_f32 v[8:9], v[8:9], v[220:221] op_sel_hi:[1,0]
	v_pk_mul_f32 v[10:11], v[10:11], v[220:221] op_sel_hi:[1,0]
	v_pk_mul_f32 v[4:5], v[4:5], v[220:221] op_sel_hi:[1,0]
	v_pk_mul_f32 v[6:7], v[6:7], v[220:221] op_sel_hi:[1,0]
	v_pk_add_f32 v[162:163], v[162:163], v[156:157]
	v_pk_add_f32 v[164:165], v[164:165], v[156:157]
	v_pk_add_f32 v[166:167], v[166:167], v[156:157]
	v_pk_add_f32 v[168:169], v[168:169], v[156:157]
	v_rcp_f32_e32 v162, v162
	v_rcp_f32_e32 v163, v163
	v_rcp_f32_e32 v164, v164
	v_rcp_f32_e32 v165, v165
	v_rcp_f32_e32 v166, v166
	v_rcp_f32_e32 v167, v167
	v_rcp_f32_e32 v168, v168
	v_rcp_f32_e32 v169, v169
	v_pk_mul_f32 v[16:17], v[16:17], v[8:9]
	v_pk_mul_f32 v[18:19], v[18:19], v[10:11]
	v_pk_mul_f32 v[12:13], v[12:13], v[4:5]
	v_pk_mul_f32 v[14:15], v[14:15], v[6:7]
	v_pk_mul_f32 v[16:17], v[16:17], v[162:163]
	v_pk_mul_f32 v[18:19], v[18:19], v[164:165]
	v_pk_mul_f32 v[12:13], v[12:13], v[166:167]
	v_pk_mul_f32 v[14:15], v[14:15], v[168:169]
	v_cvt_pk_bf16_f32 v186, v16, v17
	v_cvt_pk_bf16_f32 v187, v18, v19
	v_cvt_pk_bf16_f32 v188, v12, v13
	v_cvt_pk_bf16_f32 v189, v14, v15
	v_mov_b32_e32 v158, 0xf2000
	v_lshl_add_u64 v[160:161], v[152:153], 0, v[158:159]
	global_store_dwordx4 v[160:161], v[186:189], off
	s_cbranch_vccnz .LBB0_496
	s_branch .LBB0_495
